# V^T tile transpose-store: pair adjacent keys via DPP quad_perm + v_perm_b32 and write ds_write_b32 instead of 2x ds_write_b16 (cross/retention/diff attention)
# speedup vs baseline: 1.0268x; 1.0008x over previous
; template <int D, int DV, int MODE, int NMAP, int KT> ...
;     ...
;     { const bf16_t* qr = Qp + (size_t)(w * 16 + r) * ldq + g4 * 8;
; #pragma unroll
;       for (int mp = 0; mp < NMAP; ++mp)
; #pragma unroll
;         for (int kk = 0; kk < D / 32; ++kk) qf[mp][kk] = *(const bf16x8*)(qr + mp * D + kk * 32); }
;     float m[NMAP];
; #pragma unroll
;     for (int mp = 0; mp < NMAP; ++mp) { m[mp] = -INFINITY; l[mp] = 0.f;
; #pragma unroll
;         for (int cb = 0; cb < DV / 16; ++cb) o[mp][cb] = (f32x4){0.f, 0.f, 0.f, 0.f}; }
;     const int rowmin = q0 + w * 16, myrow = rowmin + r;
;     float ck[NB][4];
;     if (MODE == 2) {
; #pragma unroll
;         for (int nb = 0; nb < NB; ++nb)
; #pragma unroll
;             for (int j = 0; j < 4; ++j) ck[nb][j] = __builtin_amdgcn_exp2f(-l2g * (float)(nb * 16 + g4 * 4 + j));
;     }
;     u32x4 kreg[KN], vreg[VN];
; __global__ void __launch_bounds__(512, 2) mega_fwd(Params P) {
;     ...
;                     for (int u = blk; u < 2048; u += G) {
;                         const int bh = u & 127, b = bh >> 2, h = bh & 3, qt = u >> 7, q0 = qt * 128;
;                         const size_t rb = (size_t)b * SEQ;
;                         f32x4 o[1][16]; float ll[1];
;                         attn_core3<256, 256, 0, 1, 64>(lds, BIG + (rb + q0) * 1024 + h * 256, 1024, KV + (size_t)b * 256 * 2048 + h * 256, 2048, KV + (size_t)b * 256 * 2048 + 1024 + h * 256, 2048, q0, 4, 0.0625f * LOG2E, 0.f, o, ll);
.LBB0_600:
	s_lshl_b32 s4, s27, 1
	s_and_b32 s94, s4, 0x600
	s_bfe_u32 s4, s1, 0x50002
	s_and_b32 s5, s1, 0xffffff80
	s_lshl_b32 s14, s4, 20
	s_lshl_b32 s4, s4, 11
	s_ashr_i32 s6, s5, 31
	s_add_u32 s4, s4, s5
	s_addc_u32 s5, 0, s6
	s_lshl_b64 s[6:7], s[4:5], 11
	s_add_u32 s6, s21, s6
	s_addc_u32 s7, s22, s7
	s_lshl_b32 s8, s1, 8
	s_and_b32 s29, s8, 0x300
	v_mov_b32_e32 v66, v211
	s_lshl_b32 s10, s29, 1
	s_add_u32 s8, s6, s10
	v_ashrrev_i32_e32 v2, 31, v66
	v_lshrrev_b32_e32 v2, 27, v2
	s_addc_u32 s9, s7, 0
	v_add_u32_e32 v2, v66, v2
	s_add_u32 s6, s25, s14
	v_ashrrev_i32_e32 v56, 5, v2
	v_and_b32_e32 v2, 0xffffffe0, v2
	s_addc_u32 s7, s26, 0
	v_sub_u32_e32 v98, v66, v2
	s_add_u32 s12, s6, s10
	v_ashrrev_i32_e32 v57, 31, v56
	v_lshlrev_b32_e32 v4, 3, v98
	s_addc_u32 s13, s7, 0
	v_lshlrev_b64 v[2:3], 12, v[56:57]
	v_ashrrev_i32_e32 v5, 31, v4
	v_lshl_add_u64 v[6:7], s[12:13], 0, v[2:3]
	v_lshlrev_b64 v[4:5], 1, v[4:5]
	v_lshl_add_u64 v[18:19], v[6:7], 0, v[4:5]
	v_add_u32_e32 v6, 0x200, v66
	v_ashrrev_i32_e32 v7, 31, v6
	v_lshrrev_b32_e32 v7, 27, v7
	v_add_u32_e32 v7, v6, v7
	v_ashrrev_i32_e32 v58, 5, v7
	v_and_b32_e32 v7, 0xffffffe0, v7
	v_sub_u32_e32 v57, v6, v7
	v_ashrrev_i32_e32 v59, 31, v58
	v_lshlrev_b32_e32 v8, 3, v57
	v_lshlrev_b64 v[6:7], 12, v[58:59]
	v_ashrrev_i32_e32 v9, 31, v8
	v_lshl_add_u64 v[10:11], s[12:13], 0, v[6:7]
	v_lshlrev_b64 v[8:9], 1, v[8:9]
	v_lshl_add_u64 v[20:21], v[10:11], 0, v[8:9]
	v_add_u32_e32 v10, 0x400, v66
	v_ashrrev_i32_e32 v11, 31, v10
	v_lshrrev_b32_e32 v11, 27, v11
	v_add_u32_e32 v11, v10, v11
	v_ashrrev_i32_e32 v60, 5, v11
	v_and_b32_e32 v11, 0xffffffe0, v11
	v_sub_u32_e32 v59, v10, v11
	v_ashrrev_i32_e32 v61, 31, v60
	v_lshlrev_b32_e32 v12, 3, v59
	v_lshlrev_b64 v[10:11], 12, v[60:61]
	v_ashrrev_i32_e32 v13, 31, v12
	v_lshl_add_u64 v[14:15], s[12:13], 0, v[10:11]
	v_lshlrev_b64 v[12:13], 1, v[12:13]
	v_readfirstlane_b32 s6, v66
	v_lshl_add_u64 v[62:63], v[14:15], 0, v[12:13]
	v_add_u32_e32 v14, 0x600, v66
	s_ashr_i32 s15, s6, 6
	v_ashrrev_i32_e32 v15, 31, v14
	v_lshrrev_b32_e32 v15, 27, v15
	s_ashr_i32 s6, s15, 31
	v_add_u32_e32 v15, v14, v15
	s_lshr_b32 s6, s6, 27
	s_add_i32 s10, s15, 8
	v_ashrrev_i32_e32 v64, 5, v15
	s_add_i32 s6, s15, s6
	s_ashr_i32 s11, s10, 31
	v_and_b32_e32 v160, 15, v66
	v_and_b32_e32 v15, 0xffffffe0, v15
	v_ashrrev_i32_e32 v65, 31, v64
	s_ashr_i32 s31, s6, 5
	s_andn2_b32 s6, s6, 31
	s_lshr_b32 s11, s11, 27
	s_add_i32 s16, s15, 16
	v_lshl_or_b32 v54, s15, 4, v160
	v_sub_u32_e32 v61, v14, v15
	v_lshlrev_b64 v[14:15], 12, v[64:65]
	v_and_b32_e32 v65, 63, v66
	s_sub_i32 s30, s15, s6
	s_lshl_b32 s45, s31, 6
	s_add_i32 s11, s10, s11
	s_ashr_i32 s17, s16, 31
	s_add_i32 s15, s15, 24
	v_lshlrev_b32_e32 v16, 3, v61
	v_or_b32_e32 v38, s45, v65
	s_ashr_i32 s34, s11, 5
	s_lshr_b32 s17, s17, 27
	s_ashr_i32 s18, s15, 31
	global_load_dwordx4 v[22:25], v[18:19], off
	global_load_dwordx4 v[26:29], v[20:21], off
	v_ashrrev_i32_e32 v17, 31, v16
	v_ashrrev_i32_e32 v39, 31, v38
	s_lshl_b32 s6, s30, 3
	s_andn2_b32 s11, s11, 31
	s_lshl_b32 s46, s34, 6
	s_add_i32 s17, s16, s17
	s_lshr_b32 s18, s18, 27
	v_lshl_add_u64 v[30:31], s[12:13], 0, v[14:15]
	v_lshlrev_b64 v[16:17], 1, v[16:17]
	v_lshlrev_b64 v[38:39], 12, v[38:39]
	s_ashr_i32 s7, s6, 31
	s_sub_i32 s33, s10, s11
	v_or_b32_e32 v40, s46, v65
	s_ashr_i32 s41, s17, 5
	s_add_i32 s18, s15, s18
	v_lshl_add_u64 v[106:107], v[30:31], 0, v[16:17]
	global_load_dwordx4 v[30:33], v[62:63], off
	global_load_dwordx4 v[34:37], v[106:107], off
	v_lshl_add_u64 v[38:39], s[12:13], 0, v[38:39]
	s_lshl_b64 s[6:7], s[6:7], 1
	v_ashrrev_i32_e32 v41, 31, v40
	s_lshl_b32 s10, s33, 3
	s_andn2_b32 s17, s17, 31
	s_lshl_b32 s47, s41, 6
	s_ashr_i32 s43, s18, 5
	v_lshl_add_u64 v[38:39], v[38:39], 0, s[6:7]
	v_lshlrev_b64 v[40:41], 12, v[40:41]
	s_ashr_i32 s11, s10, 31
	s_sub_i32 s40, s16, s17
	v_or_b32_e32 v46, s47, v65
	s_andn2_b32 s18, s18, 31
	s_lshl_b32 s48, s43, 6
	v_lshl_add_u64 v[42:43], s[12:13], 0, v[40:41]
	global_load_dwordx4 v[38:41], v[38:39], off offset:2048
	s_lshl_b64 s[10:11], s[10:11], 1
	v_ashrrev_i32_e32 v47, 31, v46
	s_lshl_b32 s16, s40, 3
	s_sub_i32 s42, s15, s18
	v_or_b32_e32 v50, s48, v65
	v_lshl_add_u64 v[42:43], v[42:43], 0, s[10:11]
	v_lshlrev_b64 v[46:47], 12, v[46:47]
	s_ashr_i32 s17, s16, 31
	v_ashrrev_i32_e32 v51, 31, v50
	s_lshl_b32 s18, s42, 3
	global_load_dwordx4 v[42:45], v[42:43], off offset:2048
	v_lshl_add_u64 v[46:47], s[12:13], 0, v[46:47]
	s_lshl_b64 s[16:17], s[16:17], 1
	v_lshlrev_b64 v[50:51], 12, v[50:51]
	s_ashr_i32 s19, s18, 31
	v_lshl_add_u64 v[46:47], v[46:47], 0, s[16:17]
	v_lshl_add_u64 v[50:51], s[12:13], 0, v[50:51]
	s_lshl_b64 s[18:19], s[18:19], 1
	global_load_dwordx4 v[46:49], v[46:47], off offset:2048
	v_lshl_add_u64 v[50:51], v[50:51], 0, s[18:19]
	global_load_dwordx4 v[50:53], v[50:51], off offset:2048
	v_ashrrev_i32_e32 v55, 31, v54
	v_lshrrev_b32_e32 v66, 1, v66
	v_lshlrev_b64 v[54:55], 11, v[54:55]
	v_and_b32_e32 v158, 24, v66
	v_lshl_add_u64 v[54:55], s[8:9], 0, v[54:55]
	v_lshlrev_b32_e32 v148, 1, v158
	v_mov_b32_e32 v149, v1
	v_lshl_add_u64 v[54:55], v[54:55], 0, v[148:149]
	v_mul_lo_u32 v161, v56, s66
	v_lshlrev_b32_e32 v162, 4, v98
	global_load_dwordx4 v[66:69], v[54:55], off
	global_load_dwordx4 v[70:73], v[54:55], off offset:64
	global_load_dwordx4 v[74:77], v[54:55], off offset:128
	global_load_dwordx4 v[78:81], v[54:55], off offset:192
	global_load_dwordx4 v[82:85], v[54:55], off offset:256
	global_load_dwordx4 v[86:89], v[54:55], off offset:320
	global_load_dwordx4 v[90:93], v[54:55], off offset:384
	global_load_dwordx4 v[94:97], v[54:55], off offset:448
	v_lshrrev_b32_e32 v169, 2, v56
	v_lshrrev_b32_e32 v163, 3, v56
	v_xor_b32_e32 v169, v169, v163
	v_and_b32_e32 v169, 1, v169
	v_lshlrev_b32_e32 v169, 4, v169
	v_xor_b32_e32 v162, v162, v169
	v_add3_u32 v54, 0, v161, v162
	v_mul_lo_u32 v163, v58, s66
	v_lshlrev_b32_e32 v164, 4, v57
	v_xor_b32_e32 v164, v164, v169
	s_waitcnt lgkmcnt(0)
	s_barrier
; template <int D, int DV, int MODE, int NMAP, int KT> ...
;     ...
;     AT_LOAD(0);
;     __syncthreads();
;     AT_STORE(0);
;     if (nkt > 1) AT_LOAD(1);
	v_mul_lo_u32 v165, v60, s66
	v_lshlrev_b32_e32 v166, 4, v59
	v_xor_b32_e32 v166, v166, v169
	s_mulk_i32 s30, 0x480
	v_mul_lo_u32 v167, v64, s66
	v_lshlrev_b32_e32 v168, 4, v61
	v_xor_b32_e32 v168, v168, v169
	s_add_i32 s8, s30, 0
	s_lshl_b32 s31, s31, 7
	s_waitcnt vmcnt(0)
	ds_write_b128 v54, v[22:25]
	v_add3_u32 v22, 0, v163, v164
	ds_write_b128 v22, v[26:29]
	v_add3_u32 v22, 0, v165, v166
	s_add_i32 s8, s8, s31
	v_lshlrev_b32_e32 v169, 1, v65
	v_and_b32_e32 v104, 1, v65
	v_mul_u32_u24_e32 v104, 0x8e, v104
	v_add_u32_e32 v169, v169, v104
	s_mulk_i32 s33, 0x480
	s_lshl_b32 s34, s34, 7
	s_mulk_i32 s40, 0x480
	s_lshl_b32 s41, s41, 7
	s_mulk_i32 s42, 0x480
	s_lshl_b32 s43, s43, 7
	v_add_co_u32_e32 v18, vcc, s35, v18
	s_mov_b32 s15, s95
	s_nop 0
	v_addc_co_u32_e32 v19, vcc, 0, v19, vcc
	ds_write_b128 v22, v[30:33]
	v_add3_u32 v22, 0, v167, v168
	ds_write_b128 v22, v[34:37]
	v_add_u32_e32 v22, s8, v169
	s_add_i32 s8, s33, 0
	s_add_i32 s8, s8, s34
	v_bfe_i32 v103, v211, 0, 1
	v_and_b32_e32 v103, 0x6060606, v103
	v_xor_b32_e32 v103, 0x5040100, v103
	v_mov_b32_dpp v99, v38 quad_perm:[1,0,3,2] row_mask:0xf bank_mask:0xf
	v_mov_b32_dpp v100, v39 quad_perm:[1,0,3,2] row_mask:0xf bank_mask:0xf
	v_mov_b32_dpp v101, v40 quad_perm:[1,0,3,2] row_mask:0xf bank_mask:0xf
	v_mov_b32_dpp v102, v41 quad_perm:[1,0,3,2] row_mask:0xf bank_mask:0xf
	v_perm_b32 v99, v99, v38, v103
	v_perm_b32 v100, v100, v39, v103
	v_perm_b32 v101, v101, v40, v103
	v_perm_b32 v102, v102, v41, v103
	ds_write_b32 v22, v99 offset:33792
	ds_write_b32 v22, v100 offset:34080
	ds_write_b32 v22, v101 offset:34368
	ds_write_b32 v22, v102 offset:34656
	v_add_u32_e32 v22, s8, v169
	s_add_i32 s8, s40, 0
	s_add_i32 s8, s8, s41
	v_mov_b32_dpp v99, v42 quad_perm:[1,0,3,2] row_mask:0xf bank_mask:0xf
	v_mov_b32_dpp v100, v43 quad_perm:[1,0,3,2] row_mask:0xf bank_mask:0xf
	v_mov_b32_dpp v101, v44 quad_perm:[1,0,3,2] row_mask:0xf bank_mask:0xf
	v_mov_b32_dpp v102, v45 quad_perm:[1,0,3,2] row_mask:0xf bank_mask:0xf
	v_perm_b32 v99, v99, v42, v103
	v_perm_b32 v100, v100, v43, v103
	v_perm_b32 v101, v101, v44, v103
	v_perm_b32 v102, v102, v45, v103
	ds_write_b32 v22, v99 offset:33792
	ds_write_b32 v22, v100 offset:34080
	ds_write_b32 v22, v101 offset:34368
	ds_write_b32 v22, v102 offset:34656
	v_add_u32_e32 v22, s8, v169
	s_add_i32 s8, s42, 0
	s_add_i32 s8, s8, s43
	v_mov_b32_dpp v99, v46 quad_perm:[1,0,3,2] row_mask:0xf bank_mask:0xf
	v_mov_b32_dpp v100, v47 quad_perm:[1,0,3,2] row_mask:0xf bank_mask:0xf
	v_mov_b32_dpp v101, v48 quad_perm:[1,0,3,2] row_mask:0xf bank_mask:0xf
	v_mov_b32_dpp v102, v49 quad_perm:[1,0,3,2] row_mask:0xf bank_mask:0xf
	v_perm_b32 v99, v99, v46, v103
	v_perm_b32 v100, v100, v47, v103
	v_perm_b32 v101, v101, v48, v103
	v_perm_b32 v102, v102, v49, v103
	ds_write_b32 v22, v99 offset:33792
	ds_write_b32 v22, v100 offset:34080
	ds_write_b32 v22, v101 offset:34368
	ds_write_b32 v22, v102 offset:34656
	v_add_u32_e32 v22, s8, v169
	v_add_co_u32_e32 v20, vcc, s35, v20
	v_mov_b32_dpp v99, v50 quad_perm:[1,0,3,2] row_mask:0xf bank_mask:0xf
	v_mov_b32_dpp v100, v51 quad_perm:[1,0,3,2] row_mask:0xf bank_mask:0xf
	v_mov_b32_dpp v101, v52 quad_perm:[1,0,3,2] row_mask:0xf bank_mask:0xf
	v_mov_b32_dpp v102, v53 quad_perm:[1,0,3,2] row_mask:0xf bank_mask:0xf
	v_perm_b32 v99, v99, v50, v103
	v_perm_b32 v100, v100, v51, v103
	v_perm_b32 v101, v101, v52, v103
	v_perm_b32 v102, v102, v53, v103
	ds_write_b32 v22, v99 offset:33792
	ds_write_b32 v22, v100 offset:34080
	ds_write_b32 v22, v101 offset:34368
	ds_write_b32 v22, v102 offset:34656
	v_addc_co_u32_e32 v21, vcc, 0, v21, vcc
	global_load_dwordx4 v[98:101], v[18:19], off
	global_load_dwordx4 v[102:105], v[20:21], off
	v_add_co_u32_e32 v18, vcc, s35, v62
	v_or_b32_e32 v22, 64, v65
	s_nop 0
	v_addc_co_u32_e32 v19, vcc, 0, v63, vcc
	v_add_co_u32_e32 v20, vcc, s35, v106
	v_lshl_add_u64 v[14:15], s[14:15], 0, v[14:15]
	s_nop 0
	v_addc_co_u32_e32 v21, vcc, 0, v107, vcc
	global_load_dwordx4 v[106:109], v[18:19], off
	global_load_dwordx4 v[110:113], v[20:21], off
	v_add_u32_e32 v18, s45, v22
	v_ashrrev_i32_e32 v19, 31, v18
	v_add_u32_e32 v20, s46, v22
	v_lshlrev_b64 v[18:19], 12, v[18:19]
	v_ashrrev_i32_e32 v21, 31, v20
	v_lshl_add_u64 v[18:19], s[12:13], 0, v[18:19]
	v_lshlrev_b64 v[20:21], 12, v[20:21]
	v_lshl_add_u64 v[18:19], v[18:19], 0, s[6:7]
	v_lshl_add_u64 v[20:21], s[12:13], 0, v[20:21]
	v_lshl_add_u64 v[20:21], v[20:21], 0, s[10:11]
	global_load_dwordx4 v[114:117], v[18:19], off offset:2048
	global_load_dwordx4 v[118:121], v[20:21], off offset:2048
	v_add_u32_e32 v18, s47, v22
	v_ashrrev_i32_e32 v19, 31, v18
	v_add_u32_e32 v20, s48, v22
	v_lshlrev_b64 v[18:19], 12, v[18:19]
	v_ashrrev_i32_e32 v21, 31, v20
	v_lshl_add_u64 v[18:19], s[12:13], 0, v[18:19]
	v_lshlrev_b64 v[20:21], 12, v[20:21]
	v_lshl_add_u64 v[18:19], v[18:19], 0, s[16:17]
	v_lshl_add_u64 v[20:21], s[12:13], 0, v[20:21]
	v_lshl_add_u64 v[20:21], v[20:21], 0, s[18:19]
	global_load_dwordx4 v[122:125], v[18:19], off offset:2048
	global_load_dwordx4 v[126:129], v[20:21], off offset:2048
	s_add_u32 s6, s12, s6
	s_addc_u32 s7, s13, s7
	s_add_u32 s8, s12, s10
	s_addc_u32 s9, s13, s11
	s_add_u32 s10, s12, s16
	s_addc_u32 s11, s13, s17
	s_add_u32 s12, s12, s18
	v_lshl_add_u64 v[10:11], s[14:15], 0, v[10:11]
	v_lshl_add_u64 v[6:7], s[14:15], 0, v[6:7]
	v_lshl_add_u64 v[2:3], s[14:15], 0, v[2:3]
	s_addc_u32 s13, s13, s19
	s_addk_i32 s48, 0x80
	s_addk_i32 s47, 0x80
	s_addk_i32 s46, 0x80
	s_addk_i32 s45, 0x80
	v_lshl_add_u64 v[14:15], v[14:15], 0, v[16:17]
	v_lshl_add_u64 v[10:11], v[10:11], 0, v[12:13]
	v_lshl_add_u64 v[6:7], v[6:7], 0, v[8:9]
	v_lshl_add_u64 v[2:3], v[2:3], 0, v[4:5]
; template <int D, int DV, int MODE, int NMAP, int KT> ...
;     ...
;     for (int mp = 0; mp < NMAP; ++mp) { m[mp] = -INFINITY; l[mp] = 0.f;
; #pragma unroll
;         for (int cb = 0; cb < DV / 16; ++cb) o[mp][cb] = (f32x4){0.f, 0.f, 0.f, 0.f}; }
;     const int rowmin = q0 + w * 16, myrow = rowmin + r;
;     float ck[NB][4];
;     if (MODE == 2) {
; #pragma unroll
;         for (int nb = 0; nb < NB; ++nb)
; #pragma unroll
;             for (int j = 0; j < 4; ++j) ck[nb][j] = __builtin_amdgcn_exp2f(-l2g * (float)(nb * 16 + g4 * 4 + j));
;     }
;     u32x4 kreg[KN], vreg[VN];
;     ...
;     AT_LOAD(0);
;     __syncthreads();
;     AT_STORE(0);
;     if (nkt > 1) AT_LOAD(1);
;     for (int kt = 0; kt < nkt; ++kt) {
;         __syncthreads();
;         const int cur = (kt & 1) * BUF_BYTES;
;         if (kt + 1 < nkt) { AT_STORE(((kt + 1) & 1) * BUF_BYTES); if (kt + 2 < nkt) AT_LOAD(kt + 2); }
	v_mov_b32_e32 v4, v1
	v_mov_b32_e32 v5, v1
	v_or_b32_e32 v171, s48, v65
	v_or_b32_e32 v172, s47, v65
	v_or_b32_e32 v173, s46, v65
	v_or_b32_e32 v174, s45, v65
	v_lshl_add_u64 v[150:151], s[2:3], 0, v[14:15]
	v_lshl_add_u64 v[152:153], s[2:3], 0, v[10:11]
	v_lshl_add_u64 v[154:155], s[2:3], 0, v[6:7]
	v_lshl_add_u64 v[156:157], s[2:3], 0, v[2:3]
	v_mov_b32_e32 v2, v1
	v_mov_b32_e32 v3, v1
	v_mov_b64_e32 v[8:9], v[4:5]
	v_mov_b64_e32 v[12:13], v[4:5]
	v_mov_b64_e32 v[16:17], v[4:5]
	v_mov_b64_e32 v[20:21], v[4:5]
	v_mov_b64_e32 v[24:25], v[4:5]
	v_mov_b64_e32 v[28:29], v[4:5]
	v_mov_b64_e32 v[32:33], v[4:5]
	v_mov_b64_e32 v[36:37], v[4:5]
	v_mov_b64_e32 v[40:41], v[4:5]
	v_mov_b64_e32 v[44:45], v[4:5]
	v_mov_b64_e32 v[48:49], v[4:5]
	v_mov_b64_e32 v[52:53], v[4:5]
	v_mov_b64_e32 v[56:57], v[4:5]
	v_mov_b64_e32 v[60:61], v[4:5]
	v_mov_b64_e32 v[64:65], v[4:5]
	s_mov_b32 s44, 0
	v_mul_u32_u24_e32 v170, 0x210, v160
	v_lshrrev_b32_e32 v149, 2, v160
	v_lshrrev_b32_e32 v175, 3, v160
	v_xor_b32_e32 v149, v149, v175
	v_and_b32_e32 v149, 1, v149
	v_lshlrev_b32_e32 v149, 3, v149
	v_xor_b32_e32 v175, v149, v158
	v_sub_u32_e32 v175, v175, v158
	v_lshlrev_b32_e32 v175, 1, v175
	v_add_u32_e32 v170, v170, v175
	v_mul_u32_u24_e32 v149, 0x90, v160
	v_readlane_b32 s46, v254, 1
	v_mov_b32_e32 v175, 0xff800000
	v_mov_b32_e32 v159, 0
	v_mov_b64_e32 v[6:7], v[2:3]
	v_mov_b64_e32 v[10:11], v[2:3]
	v_mov_b64_e32 v[14:15], v[2:3]
	v_mov_b64_e32 v[18:19], v[2:3]
	v_mov_b64_e32 v[22:23], v[2:3]
	v_mov_b64_e32 v[26:27], v[2:3]
	v_mov_b64_e32 v[30:31], v[2:3]
	v_mov_b64_e32 v[34:35], v[2:3]
	v_mov_b64_e32 v[38:39], v[2:3]
	v_mov_b64_e32 v[42:43], v[2:3]
	v_mov_b64_e32 v[46:47], v[2:3]
	v_mov_b64_e32 v[50:51], v[2:3]
	v_mov_b64_e32 v[54:55], v[2:3]
	v_mov_b64_e32 v[58:59], v[2:3]
	v_mov_b64_e32 v[62:63], v[2:3]
	s_mov_b32 s15, 0
	v_readlane_b32 s47, v254, 2
.LBB0_601:
	s_add_i32 s14, s15, 1
	s_bitcmp1_b32 s14, 0
	s_cselect_b32 s16, 0x11400, 0
	s_add_i32 s16, s16, 0
	v_add3_u32 v130, s16, v161, v162
	s_waitcnt lgkmcnt(0)
	s_barrier
	s_waitcnt vmcnt(0)
	ds_write_b128 v130, v[98:101]
	v_add3_u32 v130, s16, v163, v164
	ds_write_b128 v130, v[102:105]
	v_add3_u32 v130, s16, v165, v166
	s_add_i32 s17, s16, s30
	ds_write_b128 v130, v[106:109]
	v_add3_u32 v130, s16, v167, v168
	s_add_i32 s17, s17, s31
	ds_write_b128 v130, v[110:113]
	v_add_u32_e32 v130, s17, v169
	s_add_i32 s17, s16, s33
	s_add_i32 s17, s17, s34
	v_bfe_i32 v230, v211, 0, 1
	v_and_b32_e32 v230, 0x6060606, v230
	v_xor_b32_e32 v230, 0x5040100, v230
	v_mov_b32_dpp v226, v114 quad_perm:[1,0,3,2] row_mask:0xf bank_mask:0xf
	v_mov_b32_dpp v227, v115 quad_perm:[1,0,3,2] row_mask:0xf bank_mask:0xf
	v_mov_b32_dpp v228, v116 quad_perm:[1,0,3,2] row_mask:0xf bank_mask:0xf
	v_mov_b32_dpp v229, v117 quad_perm:[1,0,3,2] row_mask:0xf bank_mask:0xf
	v_perm_b32 v226, v226, v114, v230
	v_perm_b32 v227, v227, v115, v230
	v_perm_b32 v228, v228, v116, v230
	v_perm_b32 v229, v229, v117, v230
	ds_write_b32 v130, v226 offset:33792
	ds_write_b32 v130, v227 offset:34080
	ds_write_b32 v130, v228 offset:34368
	ds_write_b32 v130, v229 offset:34656
	v_add_u32_e32 v130, s17, v169
	s_add_i32 s17, s16, s40
	s_add_i32 s17, s17, s41
	s_add_i32 s16, s16, s42
	v_mov_b32_dpp v226, v118 quad_perm:[1,0,3,2] row_mask:0xf bank_mask:0xf
	v_mov_b32_dpp v227, v119 quad_perm:[1,0,3,2] row_mask:0xf bank_mask:0xf
	v_mov_b32_dpp v228, v120 quad_perm:[1,0,3,2] row_mask:0xf bank_mask:0xf
	v_mov_b32_dpp v229, v121 quad_perm:[1,0,3,2] row_mask:0xf bank_mask:0xf
	v_perm_b32 v226, v226, v118, v230
	v_perm_b32 v227, v227, v119, v230
	v_perm_b32 v228, v228, v120, v230
	v_perm_b32 v229, v229, v121, v230
	ds_write_b32 v130, v226 offset:33792
	ds_write_b32 v130, v227 offset:34080
	ds_write_b32 v130, v228 offset:34368
	ds_write_b32 v130, v229 offset:34656
	v_add_u32_e32 v130, s17, v169
	s_add_i32 s16, s16, s43
	v_mov_b32_dpp v226, v122 quad_perm:[1,0,3,2] row_mask:0xf bank_mask:0xf
	v_mov_b32_dpp v227, v123 quad_perm:[1,0,3,2] row_mask:0xf bank_mask:0xf
	v_mov_b32_dpp v228, v124 quad_perm:[1,0,3,2] row_mask:0xf bank_mask:0xf
	v_mov_b32_dpp v229, v125 quad_perm:[1,0,3,2] row_mask:0xf bank_mask:0xf
	v_perm_b32 v226, v226, v122, v230
	v_perm_b32 v227, v227, v123, v230
	v_perm_b32 v228, v228, v124, v230
	v_perm_b32 v229, v229, v125, v230
	ds_write_b32 v130, v226 offset:33792
	ds_write_b32 v130, v227 offset:34080
	ds_write_b32 v130, v228 offset:34368
	ds_write_b32 v130, v229 offset:34656
	v_add_u32_e32 v130, s16, v169
	s_cmp_gt_u32 s15, 1
	v_mov_b32_dpp v226, v126 quad_perm:[1,0,3,2] row_mask:0xf bank_mask:0xf
	v_mov_b32_dpp v227, v127 quad_perm:[1,0,3,2] row_mask:0xf bank_mask:0xf
	v_mov_b32_dpp v228, v128 quad_perm:[1,0,3,2] row_mask:0xf bank_mask:0xf
	v_mov_b32_dpp v229, v129 quad_perm:[1,0,3,2] row_mask:0xf bank_mask:0xf
	v_perm_b32 v226, v226, v126, v230
	v_perm_b32 v227, v227, v127, v230
	v_perm_b32 v228, v228, v128, v230
	v_perm_b32 v229, v229, v129, v230
	ds_write_b32 v130, v226 offset:33792
	ds_write_b32 v130, v227 offset:34080
	ds_write_b32 v130, v228 offset:34368
	ds_write_b32 v130, v229 offset:34656
	s_cbranch_scc1 .LBB0_603
	v_add_u32_e32 v114, s44, v174
	v_add_u32_e32 v116, s44, v173
	v_add_u32_e32 v122, s44, v172
	v_add_u32_e32 v124, s44, v171
	v_ashrrev_i32_e32 v115, 31, v114
	v_ashrrev_i32_e32 v117, 31, v116
	v_ashrrev_i32_e32 v123, 31, v122
	v_ashrrev_i32_e32 v125, 31, v124
	v_lshlrev_b64 v[114:115], 12, v[114:115]
	v_lshlrev_b64 v[116:117], 12, v[116:117]
	v_lshlrev_b64 v[122:123], 12, v[122:123]
	v_lshlrev_b64 v[124:125], 12, v[124:125]
	v_lshl_add_u64 v[98:99], v[156:157], 0, s[94:95]
	v_lshl_add_u64 v[102:103], v[154:155], 0, s[94:95]
	v_lshl_add_u64 v[106:107], v[152:153], 0, s[94:95]
	v_lshl_add_u64 v[110:111], v[150:151], 0, s[94:95]
	v_lshl_add_u64 v[114:115], s[6:7], 0, v[114:115]
	v_lshl_add_u64 v[118:119], s[8:9], 0, v[116:117]
	v_lshl_add_u64 v[122:123], s[10:11], 0, v[122:123]
	v_lshl_add_u64 v[126:127], s[12:13], 0, v[124:125]
	global_load_dwordx4 v[98:101], v[98:99], off
	s_nop 0
	global_load_dwordx4 v[102:105], v[102:103], off
	s_nop 0
	global_load_dwordx4 v[106:109], v[106:107], off
	s_nop 0
	global_load_dwordx4 v[110:113], v[110:111], off
	s_nop 0
	global_load_dwordx4 v[114:117], v[114:115], off offset:2048
	s_nop 0
	global_load_dwordx4 v[118:121], v[118:119], off offset:2048
	s_nop 0
	global_load_dwordx4 v[122:125], v[122:123], off offset:2048
	s_nop 0
	global_load_dwordx4 v[126:129], v[126:127], off offset:2048

; template <int D, int DV, int MODE, int NMAP, int KT> ...
;     ...
;     { const bf16_t* qr = Qp + (size_t)(w * 16 + r) * ldq + g4 * 8;
; #pragma unroll
;       for (int mp = 0; mp < NMAP; ++mp)
; #pragma unroll
;         for (int kk = 0; kk < D / 32; ++kk) qf[mp][kk] = *(const bf16x8*)(qr + mp * D + kk * 32); }
;     float m[NMAP];
; #pragma unroll
;     for (int mp = 0; mp < NMAP; ++mp) { m[mp] = -INFINITY; l[mp] = 0.f;
; #pragma unroll
;         for (int cb = 0; cb < DV / 16; ++cb) o[mp][cb] = (f32x4){0.f, 0.f, 0.f, 0.f}; }
;     const int rowmin = q0 + w * 16, myrow = rowmin + r;
;     float ck[NB][4];
;     if (MODE == 2) {
; #pragma unroll
;         for (int nb = 0; nb < NB; ++nb)
; #pragma unroll
;             for (int j = 0; j < 4; ++j) ck[nb][j] = __builtin_amdgcn_exp2f(-l2g * (float)(nb * 16 + g4 * 4 + j));
;     }
;     u32x4 kreg[KN], vreg[VN];
; __global__ void __launch_bounds__(512, 2) mega_fwd(Params P) {
;     ...
;                             const int bh = u & 127, b = bh >> 2, h = bh & 3, qi_ = u >> 7, ii_ = qi_ >> 1, hb_ = qi_ & 1, qt = (ii_ & 1) ? (ii_ - 1 + hb_) : (15 - hb_ - ii_), q0 = qt * 128, nkt = qt + 1;
;                             const size_t rb = (size_t)b * SEQ;
;                             const float l2g = log2f(1.0f - exp2f(-5.0f - (float)h));
;                             f32x4 o[1][8]; float ll[1];
;                             attn_core3<64, 128, 2, 1, 128>(lds, Z + (rb + q0) * ZW + 512 + h * 64, ZW, Z + rb * ZW + 768 + h * 64, ZW, Z + rb * ZW + 1024 + h * 128, ZW, q0, nkt, 1.0f, l2g, o, ll);
.LBB0_788:
	s_ashr_i32 s6, s1, 8
	s_bfe_u32 s7, s1, 0x10007
	s_add_i32 s9, s6, s7
	s_xor_b32 s7, s7, 15
	s_and_b32 s12, s1, 3
	s_and_b32 s8, s1, 0x100
	s_add_i32 s9, s9, -1
	s_sub_i32 s6, s7, s6
	s_cmp_eq_u32 s8, 0
	s_cselect_b32 s22, s6, s9
	s_lshl_b32 s6, s1, 9
	v_cvt_f32_ubyte0_e32 v0, s12
	s_and_b32 s8, s6, 0xf800
	v_sub_f32_e32 v0, 0xc0a00000, v0
	s_mov_b32 s6, 0xc2fc0000
	v_cmp_gt_f32_e32 vcc, s6, v0
	v_mov_b32_e32 v2, 0x42800000
	s_lshl_b32 s31, s22, 7
	v_cndmask_b32_e32 v2, 0, v2, vcc
	v_add_f32_e32 v0, v0, v2
	v_exp_f32_e32 v0, v0
	s_and_b64 s[6:7], vcc, exec
	s_cselect_b32 s6, 0xffffffc0, 0
	v_mov_b32_e32 v11, v211
	v_ldexp_f32 v0, v0, s6
	v_sub_f32_e32 v10, 1.0, v0
	v_cmp_gt_f32_e32 vcc, s50, v10
	s_and_b64 s[6:7], vcc, exec
	s_cselect_b32 s43, 32, 0
	s_ashr_i32 s7, s31, 31
	s_add_u32 s6, s31, s8
	s_addc_u32 s7, s7, 0
	s_mul_i32 s9, s7, 0x1400
	s_mul_hi_u32 s10, s6, 0x1400
	s_add_i32 s10, s10, s9
	s_mul_i32 s9, s6, 0x1400
	s_add_u32 s9, s4, s9
	s_addc_u32 s11, s5, s10
	s_lshl_b32 s21, s12, 7
	s_add_u32 s10, s9, s21
	s_addc_u32 s11, s11, 0
	s_mulk_i32 s8, 0x1400
	s_add_u32 s13, s4, s8
	s_addc_u32 s15, s5, 0
	s_add_u32 s8, s13, s21
	s_addc_u32 s9, s15, 0
	s_lshl_b32 s12, s12, 8
	s_add_u32 s14, s13, s12
	s_addc_u32 s15, s15, 0
	v_readfirstlane_b32 s12, v11
	s_ashr_i32 s18, s12, 6
	v_and_b32_e32 v6, 15, v11
	s_lshl_b32 s33, s18, 4
	v_or_b32_e32 v0, s33, v6
	v_mov_b64_e32 v[2:3], s[10:11]
	v_mad_i64_i32 v[2:3], s[10:11], v0, s57, v[2:3]
	v_and_b32_e32 v0, 48, v11
	v_lshl_add_u64 v[2:3], v[2:3], 0, v[0:1]
	v_ashrrev_i32_e32 v0, 31, v11
	v_lshrrev_b32_e32 v0, 29, v0
	v_add_u32_e32 v0, v11, v0
	v_ashrrev_i32_e32 v8, 3, v0
	v_and_b32_e32 v0, -8, v0
	v_sub_u32_e32 v16, v11, v0
	global_load_dwordx4 v[34:37], v[2:3], off offset:1024
	global_load_dwordx4 v[38:41], v[2:3], off offset:1088
	v_mov_b64_e32 v[4:5], s[8:9]
	v_lshlrev_b32_e32 v2, 3, v16
	v_add_u32_e32 v0, 0x200, v11
	v_mad_i64_i32 v[12:13], s[10:11], v8, s57, v[4:5]
	v_ashrrev_i32_e32 v3, 31, v2
	v_ashrrev_i32_e32 v9, 31, v0
	v_lshl_add_u64 v[12:13], v[2:3], 1, v[12:13]
	v_lshrrev_b32_e32 v9, 29, v9
	global_load_dwordx4 v[42:45], v[12:13], off offset:1536
	v_add_u32_e32 v12, v0, v9
	v_ashrrev_i32_e32 v9, 3, v12
	v_and_b32_e32 v12, -8, v12
	v_sub_u32_e32 v17, v0, v12
	v_mad_i64_i32 v[12:13], s[10:11], v9, s57, v[4:5]
	s_ashr_i32 s10, s18, 31
	s_lshr_b32 s10, s10, 28
	v_lshlrev_b32_e32 v4, 3, v17
	s_add_i32 s10, s18, s10
	v_ashrrev_i32_e32 v5, 31, v4
	s_ashr_i32 s24, s10, 4
	s_add_i32 s12, s18, 8
	v_and_b32_e32 v7, 63, v11
	v_lshl_add_u64 v[12:13], v[4:5], 1, v[12:13]
	s_lshl_b32 s34, s24, 6
	s_ashr_i32 s13, s12, 31
	global_load_dwordx4 v[46:49], v[12:13], off offset:1536
	s_and_b32 s10, s10, -16
	v_or_b32_e32 v0, s34, v7
	v_mov_b64_e32 v[12:13], s[14:15]
	s_lshr_b32 s13, s13, 28
	s_sub_i32 s23, s18, s10
	v_mad_i64_i32 v[14:15], s[10:11], v0, s57, v[12:13]
	s_add_i32 s13, s12, s13
	s_lshl_b32 s10, s23, 3
	s_ashr_i32 s26, s13, 4
	s_add_i32 s16, s18, 16
	s_ashr_i32 s11, s10, 31
	s_lshl_b32 s40, s26, 6
	s_ashr_i32 s17, s16, 31
	s_add_i32 s18, s18, 24
	v_lshl_add_u64 v[14:15], s[10:11], 1, v[14:15]
	s_and_b32 s13, s13, -16
	v_or_b32_e32 v0, s40, v7
	s_lshr_b32 s17, s17, 28
	s_ashr_i32 s19, s18, 31
	global_load_dwordx4 v[50:53], v[14:15], off offset:2048
	s_sub_i32 s25, s12, s13
	v_mad_i64_i32 v[14:15], s[12:13], v0, s57, v[12:13]
	s_add_i32 s17, s16, s17
	s_lshr_b32 s19, s19, 28
	s_lshl_b32 s12, s25, 3
	s_ashr_i32 s28, s17, 4
	s_add_i32 s19, s18, s19
	s_ashr_i32 s13, s12, 31
	s_lshl_b32 s41, s28, 6
	s_ashr_i32 s30, s19, 4
	v_lshl_add_u64 v[14:15], s[12:13], 1, v[14:15]
	s_and_b32 s17, s17, -16
	v_or_b32_e32 v0, s41, v7
	s_lshl_b32 s42, s30, 6
	global_load_dwordx4 v[54:57], v[14:15], off offset:2048
	s_sub_i32 s27, s16, s17
	v_mad_i64_i32 v[14:15], s[16:17], v0, s57, v[12:13]
	s_and_b32 s19, s19, -16
	v_or_b32_e32 v0, s42, v7
	s_lshl_b32 s16, s27, 3
	s_sub_i32 s29, s18, s19
	v_mad_i64_i32 v[12:13], s[18:19], v0, s57, v[12:13]
	s_ashr_i32 s17, s16, 31
	s_lshl_b32 s18, s29, 3
	v_lshl_add_u64 v[14:15], s[16:17], 1, v[14:15]
	s_ashr_i32 s19, s18, 31
	global_load_dwordx4 v[58:61], v[14:15], off offset:2048
	v_lshl_add_u64 v[12:13], s[18:19], 1, v[12:13]
	global_load_dwordx4 v[62:65], v[12:13], off offset:2048
	s_movk_i32 s36, 0x90
	v_mul_lo_u32 v0, v8, s36
	v_lshlrev_b32_e32 v79, 4, v16
	v_lshrrev_b32_e32 v12, 2, v8
	v_lshrrev_b32_e32 v86, 3, v8
	v_xor_b32_e32 v86, v12, v86
	v_and_b32_e32 v86, 1, v86
	v_lshlrev_b32_e32 v86, 4, v86
	v_xor_b32_e32 v79, v79, v86
	s_mulk_i32 s23, 0x880
	v_add3_u32 v12, 0, v0, v79
	v_mul_lo_u32 v84, v9, s36
	v_lshlrev_b32_e32 v85, 4, v17
	v_xor_b32_e32 v85, v85, v86
	s_add_i32 s44, s23, 0
	s_lshl_b32 s24, s24, 7
	s_waitcnt lgkmcnt(0)
	s_barrier
; template <int D, int DV, int MODE, int NMAP, int KT> ...
;     ...
;     AT_LOAD(0);
;     __syncthreads();
;     AT_STORE(0);
;     if (nkt > 1) AT_LOAD(1);
	s_waitcnt vmcnt(0)
	ds_write_b128 v12, v[42:45]
	v_add3_u32 v12, 0, v84, v85
	s_add_i32 s44, s44, s24
	v_lshlrev_b32_e32 v86, 1, v7
	v_and_b32_e32 v245, 1, v7
	v_mul_u32_u24_e32 v245, 0x10e, v245
	v_add_u32_e32 v86, v86, v245
	s_mulk_i32 s25, 0x880
	s_lshl_b32 s26, s26, 7
	s_mulk_i32 s27, 0x880
	s_lshl_b32 s28, s28, 7
	s_mulk_i32 s29, 0x880
	s_lshl_b32 s30, s30, 7
	ds_write_b128 v12, v[46:49]
	v_add_u32_e32 v12, s44, v86
	s_add_i32 s44, s25, 0
	s_add_i32 s44, s44, s26
	v_bfe_i32 v244, v211, 0, 1
	v_and_b32_e32 v244, 0x6060606, v244
	v_xor_b32_e32 v244, 0x5040100, v244
	v_mov_b32_dpp v240, v50 quad_perm:[1,0,3,2] row_mask:0xf bank_mask:0xf
	v_mov_b32_dpp v241, v51 quad_perm:[1,0,3,2] row_mask:0xf bank_mask:0xf
	v_mov_b32_dpp v242, v52 quad_perm:[1,0,3,2] row_mask:0xf bank_mask:0xf
	v_mov_b32_dpp v243, v53 quad_perm:[1,0,3,2] row_mask:0xf bank_mask:0xf
	v_perm_b32 v240, v240, v50, v244
	v_perm_b32 v241, v241, v51, v244
	v_perm_b32 v242, v242, v52, v244
	v_perm_b32 v243, v243, v53, v244
	ds_write_b32 v12, v240 offset:18432
	ds_write_b32 v12, v241 offset:18976
	ds_write_b32 v12, v242 offset:19520
	ds_write_b32 v12, v243 offset:20064
	v_add_u32_e32 v12, s44, v86
	s_add_i32 s44, s27, 0
	s_add_i32 s44, s44, s28
	v_mov_b32_dpp v240, v54 quad_perm:[1,0,3,2] row_mask:0xf bank_mask:0xf
	v_mov_b32_dpp v241, v55 quad_perm:[1,0,3,2] row_mask:0xf bank_mask:0xf
	v_mov_b32_dpp v242, v56 quad_perm:[1,0,3,2] row_mask:0xf bank_mask:0xf
	v_mov_b32_dpp v243, v57 quad_perm:[1,0,3,2] row_mask:0xf bank_mask:0xf
	v_perm_b32 v240, v240, v54, v244
	v_perm_b32 v241, v241, v55, v244
	v_perm_b32 v242, v242, v56, v244
	v_perm_b32 v243, v243, v57, v244
	ds_write_b32 v12, v240 offset:18432
	ds_write_b32 v12, v241 offset:18976
	ds_write_b32 v12, v242 offset:19520
	ds_write_b32 v12, v243 offset:20064
	v_add_u32_e32 v12, s44, v86
	s_add_i32 s44, s29, 0
	s_add_i32 s44, s44, s30
	v_mov_b32_dpp v240, v58 quad_perm:[1,0,3,2] row_mask:0xf bank_mask:0xf
	v_mov_b32_dpp v241, v59 quad_perm:[1,0,3,2] row_mask:0xf bank_mask:0xf
	v_mov_b32_dpp v242, v60 quad_perm:[1,0,3,2] row_mask:0xf bank_mask:0xf
	v_mov_b32_dpp v243, v61 quad_perm:[1,0,3,2] row_mask:0xf bank_mask:0xf
	v_perm_b32 v240, v240, v58, v244
	v_perm_b32 v241, v241, v59, v244
	v_perm_b32 v242, v242, v60, v244
	v_perm_b32 v243, v243, v61, v244
	ds_write_b32 v12, v240 offset:18432
	ds_write_b32 v12, v241 offset:18976
	ds_write_b32 v12, v242 offset:19520
	ds_write_b32 v12, v243 offset:20064
	v_add_u32_e32 v12, s44, v86
	s_cmp_lt_i32 s22, 1
	v_mov_b32_dpp v240, v62 quad_perm:[1,0,3,2] row_mask:0xf bank_mask:0xf
	v_mov_b32_dpp v241, v63 quad_perm:[1,0,3,2] row_mask:0xf bank_mask:0xf
	v_mov_b32_dpp v242, v64 quad_perm:[1,0,3,2] row_mask:0xf bank_mask:0xf
	v_mov_b32_dpp v243, v65 quad_perm:[1,0,3,2] row_mask:0xf bank_mask:0xf
	v_perm_b32 v240, v240, v62, v244
	v_perm_b32 v241, v241, v63, v244
	v_perm_b32 v242, v242, v64, v244
	v_perm_b32 v243, v243, v65, v244
	ds_write_b32 v12, v240 offset:18432
	ds_write_b32 v12, v241 offset:18976
	ds_write_b32 v12, v242 offset:19520
	ds_write_b32 v12, v243 offset:20064
	s_cbranch_scc1 .LBB0_790
	v_add_u32_e32 v14, 0x80, v8
	v_mov_b64_e32 v[12:13], s[8:9]
	v_add_u32_e32 v16, 0x80, v9
	v_mad_i64_i32 v[14:15], s[44:45], v14, s57, v[12:13]
	v_mad_i64_i32 v[12:13], s[44:45], v16, s57, v[12:13]
	v_lshl_add_u64 v[14:15], v[2:3], 1, v[14:15]
	v_lshl_add_u64 v[12:13], v[4:5], 1, v[12:13]
	v_or_b32_e32 v18, 0x80, v7
	global_load_dwordx4 v[42:45], v[14:15], off offset:1536
	global_load_dwordx4 v[46:49], v[12:13], off offset:1536
	v_add_u32_e32 v14, s34, v18
	v_mov_b64_e32 v[12:13], s[14:15]
	v_mad_i64_i32 v[14:15], s[44:45], v14, s57, v[12:13]
	v_add_u32_e32 v16, s40, v18
	v_lshl_add_u64 v[14:15], s[10:11], 1, v[14:15]
	v_mad_i64_i32 v[16:17], s[44:45], v16, s57, v[12:13]
	v_lshl_add_u64 v[16:17], s[12:13], 1, v[16:17]
	global_load_dwordx4 v[50:53], v[14:15], off offset:2048
	global_load_dwordx4 v[54:57], v[16:17], off offset:2048
	v_add_u32_e32 v14, s41, v18
	v_mad_i64_i32 v[14:15], s[44:45], v14, s57, v[12:13]
	v_add_u32_e32 v16, s42, v18
	v_lshl_add_u64 v[14:15], s[16:17], 1, v[14:15]
	v_mad_i64_i32 v[12:13], s[44:45], v16, s57, v[12:13]
	v_lshl_add_u64 v[12:13], s[18:19], 1, v[12:13]
	global_load_dwordx4 v[58:61], v[14:15], off offset:2048
	global_load_dwordx4 v[62:65], v[12:13], off offset:2048

; template <int D, int DV, int MODE, int NMAP, int KT> ...
;     ...
;     AT_LOAD(0);
;     __syncthreads();
;     AT_STORE(0);
;     if (nkt > 1) AT_LOAD(1);
;     for (int kt = 0; kt < nkt; ++kt) {
;         __syncthreads();
;         const int cur = (kt & 1) * BUF_BYTES;
;         if (kt + 1 < nkt) { AT_STORE(((kt + 1) & 1) * BUF_BYTES); if (kt + 2 < nkt) AT_LOAD(kt + 2); }
.LBB0_792:
	s_add_i32 s34, s16, 1
	s_cmp_ge_i32 s16, s22
	s_waitcnt lgkmcnt(0)
	s_barrier
	s_cbranch_scc1 .LBB0_795
	s_bitcmp1_b32 s34, 0
	s_cselect_b32 s17, 0xd000, 0
	s_add_i32 s17, s17, 0
	v_add3_u32 v66, s17, v0, v79
	s_add_i32 s40, s17, s23
	s_waitcnt vmcnt(0)
	ds_write_b128 v66, v[42:45]
	v_add3_u32 v66, s17, v84, v85
	s_add_i32 s40, s40, s24
	ds_write_b128 v66, v[46:49]
	v_add_u32_e32 v66, s40, v86
	s_add_i32 s40, s17, s25
	s_add_i32 s40, s40, s26
	v_bfe_i32 v244, v211, 0, 1
	v_and_b32_e32 v244, 0x6060606, v244
	v_xor_b32_e32 v244, 0x5040100, v244
	v_mov_b32_dpp v240, v50 quad_perm:[1,0,3,2] row_mask:0xf bank_mask:0xf
	v_mov_b32_dpp v241, v51 quad_perm:[1,0,3,2] row_mask:0xf bank_mask:0xf
	v_mov_b32_dpp v242, v52 quad_perm:[1,0,3,2] row_mask:0xf bank_mask:0xf
	v_mov_b32_dpp v243, v53 quad_perm:[1,0,3,2] row_mask:0xf bank_mask:0xf
	v_perm_b32 v240, v240, v50, v244
	v_perm_b32 v241, v241, v51, v244
	v_perm_b32 v242, v242, v52, v244
	v_perm_b32 v243, v243, v53, v244
	ds_write_b32 v66, v240 offset:18432
	ds_write_b32 v66, v241 offset:18976
	ds_write_b32 v66, v242 offset:19520
	ds_write_b32 v66, v243 offset:20064
	v_add_u32_e32 v66, s40, v86
	s_add_i32 s40, s17, s27
	s_add_i32 s40, s40, s28
	s_add_i32 s17, s17, s29
	v_mov_b32_dpp v240, v54 quad_perm:[1,0,3,2] row_mask:0xf bank_mask:0xf
	v_mov_b32_dpp v241, v55 quad_perm:[1,0,3,2] row_mask:0xf bank_mask:0xf
	v_mov_b32_dpp v242, v56 quad_perm:[1,0,3,2] row_mask:0xf bank_mask:0xf
	v_mov_b32_dpp v243, v57 quad_perm:[1,0,3,2] row_mask:0xf bank_mask:0xf
	v_perm_b32 v240, v240, v54, v244
	v_perm_b32 v241, v241, v55, v244
	v_perm_b32 v242, v242, v56, v244
	v_perm_b32 v243, v243, v57, v244
	ds_write_b32 v66, v240 offset:18432
	ds_write_b32 v66, v241 offset:18976
	ds_write_b32 v66, v242 offset:19520
	ds_write_b32 v66, v243 offset:20064
	v_add_u32_e32 v66, s40, v86
	s_add_i32 s17, s17, s30
	v_mov_b32_dpp v240, v58 quad_perm:[1,0,3,2] row_mask:0xf bank_mask:0xf
	v_mov_b32_dpp v241, v59 quad_perm:[1,0,3,2] row_mask:0xf bank_mask:0xf
	v_mov_b32_dpp v242, v60 quad_perm:[1,0,3,2] row_mask:0xf bank_mask:0xf
	v_mov_b32_dpp v243, v61 quad_perm:[1,0,3,2] row_mask:0xf bank_mask:0xf
	v_perm_b32 v240, v240, v58, v244
	v_perm_b32 v241, v241, v59, v244
	v_perm_b32 v242, v242, v60, v244
	v_perm_b32 v243, v243, v61, v244
	ds_write_b32 v66, v240 offset:18432
	ds_write_b32 v66, v241 offset:18976
	ds_write_b32 v66, v242 offset:19520
	ds_write_b32 v66, v243 offset:20064
	v_add_u32_e32 v66, s17, v86
	s_add_i32 s17, s16, 2
	s_cmp_gt_i32 s17, s22
	v_mov_b32_dpp v240, v62 quad_perm:[1,0,3,2] row_mask:0xf bank_mask:0xf
	v_mov_b32_dpp v241, v63 quad_perm:[1,0,3,2] row_mask:0xf bank_mask:0xf
	v_mov_b32_dpp v242, v64 quad_perm:[1,0,3,2] row_mask:0xf bank_mask:0xf
	v_mov_b32_dpp v243, v65 quad_perm:[1,0,3,2] row_mask:0xf bank_mask:0xf
	v_perm_b32 v240, v240, v62, v244
	v_perm_b32 v241, v241, v63, v244
	v_perm_b32 v242, v242, v64, v244
	v_perm_b32 v243, v243, v65, v244
	ds_write_b32 v66, v240 offset:18432
	ds_write_b32 v66, v241 offset:18976
	ds_write_b32 v66, v242 offset:19520
	ds_write_b32 v66, v243 offset:20064
	s_cbranch_scc1 .LBB0_795
	v_add_u32_e32 v52, s19, v131
	v_mov_b64_e32 v[50:51], s[8:9]
	v_add_u32_e32 v60, s19, v129
	v_mov_b64_e32 v[58:59], s[12:13]
	v_add_u32_e32 v42, s19, v133
	v_add_u32_e32 v44, s19, v132
	v_mad_i64_i32 v[50:51], s[40:41], v52, s57, v[50:51]
	v_add_u32_e32 v54, s19, v130
	v_mov_b64_e32 v[52:53], s[10:11]
	v_mad_i64_i32 v[58:59], s[40:41], v60, s57, v[58:59]
	v_add_u32_e32 v62, s19, v128
	v_mov_b64_e32 v[60:61], s[14:15]
	v_mad_i64_i32 v[42:43], s[40:41], v42, s57, v[80:81]
	v_mad_i64_i32 v[46:47], s[40:41], v44, s57, v[82:83]
	v_mad_i64_i32 v[54:55], s[40:41], v54, s57, v[52:53]
	v_mad_i64_i32 v[62:63], s[40:41], v62, s57, v[60:61]
	global_load_dwordx4 v[42:45], v[42:43], off offset:1536
	s_nop 0
	global_load_dwordx4 v[46:49], v[46:47], off offset:1536
	s_nop 0
	global_load_dwordx4 v[50:53], v[50:51], off offset:2048
	s_nop 0
	global_load_dwordx4 v[54:57], v[54:55], off offset:2048
	s_nop 0
	global_load_dwordx4 v[58:61], v[58:59], off offset:2048
	s_nop 0
	global_load_dwordx4 v[62:65], v[62:63], off offset:2048

; template <int D, int DV, int MODE, int NMAP, int KT> ...
;     ...
;     { const bf16_t* qr = Qp + (size_t)(w * 16 + r) * ldq + g4 * 8;
; #pragma unroll
;       for (int mp = 0; mp < NMAP; ++mp)
; #pragma unroll
;         for (int kk = 0; kk < D / 32; ++kk) qf[mp][kk] = *(const bf16x8*)(qr + mp * D + kk * 32); }
;     float m[NMAP];
; #pragma unroll
;     for (int mp = 0; mp < NMAP; ++mp) { m[mp] = -INFINITY; l[mp] = 0.f;
; #pragma unroll
;         for (int cb = 0; cb < DV / 16; ++cb) o[mp][cb] = (f32x4){0.f, 0.f, 0.f, 0.f}; }
;     const int rowmin = q0 + w * 16, myrow = rowmin + r;
;     float ck[NB][4];
;     if (MODE == 2) {
; #pragma unroll
;         for (int nb = 0; nb < NB; ++nb)
; #pragma unroll
;             for (int j = 0; j < 4; ++j) ck[nb][j] = __builtin_amdgcn_exp2f(-l2g * (float)(nb * 16 + g4 * 4 + j));
;     }
;     u32x4 kreg[KN], vreg[VN];
;     ...
;     AT_LOAD(0);
;     __syncthreads();
;     AT_STORE(0);
;     if (nkt > 1) AT_LOAD(1);
; __global__ void __launch_bounds__(512, 2) mega_fwd(Params P) {
;     ...
;                             const int bh = u & 127, b = bh >> 2, h = bh & 3, qi_ = u >> 7, ii_ = qi_ >> 1, hb_ = qi_ & 1, qt = (ii_ & 1) ? (ii_ - 1 + hb_) : (15 - hb_ - ii_), q0 = qt * 128, nkt = (q0 + 128) / 64;
;                             const size_t rb = (size_t)b * SEQ;
;                             f32x4 o[2][8]; float ll[2];
;                             attn_core3<64, 128, 1, 2, 64>(lds, Z + (rb + q0) * ZW + h * 128, ZW, Z + rb * ZW + 512 + h * 128, ZW, Z + rb * ZW + 1024 + h * 128, ZW, q0, nkt, 0.125f * LOG2E, 0.f, o, ll);
.LBB0_1089:
	s_ashr_i32 s2, s1, 8
	s_bfe_u32 s3, s1, 0x10007
	s_add_i32 s5, s2, s3
	s_xor_b32 s3, s3, 15
	s_and_b32 s4, s1, 0x100
	s_add_i32 s5, s5, -1
	s_sub_i32 s2, s3, s2
	s_cmp_eq_u32 s4, 0
	s_cselect_b32 s2, s2, s5
	s_lshl_b32 s8, s2, 7
	s_add_i32 s2, s8, 0x80
	s_ashr_i32 s44, s2, 6
	s_lshl_b32 s2, s1, 9
	s_and_b32 s2, s2, 0xf800
	s_ashr_i32 s3, s8, 31
	s_add_u32 s46, s8, s2
	s_addc_u32 s47, s3, 0
	s_mul_i32 s3, s47, 0x1400
	s_mul_hi_u32 s4, s46, 0x1400
	s_add_i32 s4, s4, s3
	s_mul_i32 s3, s46, 0x1400
	s_add_u32 s3, s34, s3
	s_addc_u32 s5, s40, s4
	s_lshl_b32 s4, s1, 7
	s_and_b32 s4, s4, 0x180
	s_lshl_b32 s43, s4, 1
	s_add_u32 s4, s3, s43
	s_addc_u32 s5, s5, 0
	s_mulk_i32 s2, 0x1400
	s_add_u32 s2, s34, s2
	s_addc_u32 s3, s40, 0
	v_mov_b32_e32 v28, v211
	s_add_u32 s2, s2, s43
	s_addc_u32 s3, s3, 0
	v_readfirstlane_b32 s6, v28
	s_ashr_i32 s6, s6, 6
	v_and_b32_e32 v27, 15, v28
	s_lshl_b32 s74, s6, 4
	v_or_b32_e32 v0, s74, v27
	v_mov_b64_e32 v[2:3], s[4:5]
	v_mad_i64_i32 v[2:3], s[4:5], v0, s57, v[2:3]
	v_and_b32_e32 v0, 48, v28
	v_add_u32_e32 v24, 0x200, v28
	v_lshl_add_u64 v[14:15], v[2:3], 0, v[0:1]
	v_ashrrev_i32_e32 v0, 31, v28
	v_ashrrev_i32_e32 v25, 31, v24
	v_lshrrev_b32_e32 v0, 28, v0
	v_lshrrev_b32_e32 v25, 28, v25
	v_add_u32_e32 v18, v28, v0
	v_add_u32_e32 v25, v24, v25
	v_ashrrev_i32_e32 v0, 4, v18
	v_and_b32_e32 v18, -16, v18
	v_mov_b64_e32 v[34:35], s[2:3]
	v_ashrrev_i32_e32 v29, 4, v25
	v_sub_u32_e32 v38, v28, v18
	v_mad_i64_i32 v[18:19], s[4:5], v0, s57, v[34:35]
	v_mad_i64_i32 v[30:31], s[4:5], v29, s57, v[34:35]
	s_ashr_i32 s4, s6, 31
	s_lshr_b32 s4, s4, 28
	s_add_i32 s4, s6, s4
	s_ashr_i32 s11, s4, 4
	s_and_b32 s4, s4, -16
	v_and_b32_e32 v26, 63, v28
	s_sub_i32 s45, s6, s4
	s_lshl_b32 s9, s11, 6
	s_add_i32 s6, s6, 8
	v_or_b32_e32 v36, s9, v26
	s_ashr_i32 s7, s6, 31
	v_mad_i64_i32 v[36:37], s[4:5], v36, s57, v[34:35]
	s_lshr_b32 s7, s7, 28
	s_lshl_b32 s4, s45, 3
	s_add_i32 s7, s6, s7
	v_and_b32_e32 v25, -16, v25
	s_ashr_i32 s5, s4, 31
	s_ashr_i32 s12, s7, 4
	v_lshlrev_b32_e32 v22, 3, v38
	v_sub_u32_e32 v39, v24, v25
	v_lshl_add_u64 v[36:37], s[4:5], 1, v[36:37]
	s_lshl_b32 s10, s12, 6
	global_load_dwordx4 v[2:5], v[14:15], off
	global_load_dwordx4 v[6:9], v[14:15], off offset:64
	global_load_dwordx4 v[10:13], v[14:15], off offset:128
	s_nop 0
	global_load_dwordx4 v[14:17], v[14:15], off offset:192
	v_ashrrev_i32_e32 v23, 31, v22
	v_lshlrev_b32_e32 v24, 3, v39
	global_load_dwordx4 v[58:61], v[36:37], off offset:2048
	s_and_b32 s7, s7, -16
	v_or_b32_e32 v36, s10, v26
	v_lshl_add_u64 v[18:19], v[22:23], 1, v[18:19]
	v_ashrrev_i32_e32 v25, 31, v24
	s_sub_i32 s61, s6, s7
	v_mad_i64_i32 v[34:35], s[6:7], v36, s57, v[34:35]
	global_load_dwordx4 v[18:21], v[18:19], off offset:1024
	v_lshl_add_u64 v[30:31], v[24:25], 1, v[30:31]
	s_lshl_b32 s6, s61, 3
	global_load_dwordx4 v[30:33], v[30:31], off offset:1024
	s_ashr_i32 s7, s6, 31
	v_lshl_add_u64 v[34:35], s[6:7], 1, v[34:35]
	global_load_dwordx4 v[62:65], v[34:35], off offset:2048
	s_movk_i32 s13, 0x110
	v_mul_lo_u32 v135, v0, s13
	v_lshlrev_b32_e32 v144, 4, v38
	v_lshrrev_b32_e32 v34, 2, v0
	v_lshrrev_b32_e32 v147, 3, v0
	v_xor_b32_e32 v147, v34, v147
	v_and_b32_e32 v147, 1, v147
	v_lshlrev_b32_e32 v147, 4, v147
	v_xor_b32_e32 v144, v144, v147
	s_mulk_i32 s45, 0x480
	v_add3_u32 v34, 0, v135, v144
	v_mul_lo_u32 v145, v29, s13
	v_lshlrev_b32_e32 v146, 4, v39
	v_xor_b32_e32 v146, v146, v147
	s_add_i32 s13, s45, 0
	s_lshl_b32 s56, s11, 7
	s_mulk_i32 s61, 0x480
	s_waitcnt lgkmcnt(0)
	s_barrier
	s_add_i32 s13, s13, s56
	v_lshlrev_b32_e32 v147, 1, v26
	v_and_b32_e32 v245, 1, v26
	v_mul_u32_u24_e32 v245, 0x8e, v245
	v_add_u32_e32 v147, v147, v245
	s_add_i32 s11, s61, 0
	s_lshl_b32 s67, s12, 7
	s_add_i32 s11, s11, s67
	s_cmp_lt_i32 s44, 2
	s_waitcnt vmcnt(0)
	ds_write_b128 v34, v[18:21]
	v_add3_u32 v34, 0, v145, v146
	ds_write_b128 v34, v[30:33]
	v_add_u32_e32 v34, s13, v147
	v_bfe_i32 v244, v211, 0, 1
	v_and_b32_e32 v244, 0x6060606, v244
	v_xor_b32_e32 v244, 0x5040100, v244
	v_mov_b32_dpp v240, v58 quad_perm:[1,0,3,2] row_mask:0xf bank_mask:0xf
	v_mov_b32_dpp v241, v59 quad_perm:[1,0,3,2] row_mask:0xf bank_mask:0xf
	v_mov_b32_dpp v242, v60 quad_perm:[1,0,3,2] row_mask:0xf bank_mask:0xf
	v_mov_b32_dpp v243, v61 quad_perm:[1,0,3,2] row_mask:0xf bank_mask:0xf
	v_perm_b32 v240, v240, v58, v244
	v_perm_b32 v241, v241, v59, v244
	v_perm_b32 v242, v242, v60, v244
	v_perm_b32 v243, v243, v61, v244
	ds_write_b32 v34, v240 offset:17408
	ds_write_b32 v34, v241 offset:17696
	ds_write_b32 v34, v242 offset:17984
	ds_write_b32 v34, v243 offset:18272
	v_add_u32_e32 v34, s11, v147
	v_mov_b32_dpp v240, v62 quad_perm:[1,0,3,2] row_mask:0xf bank_mask:0xf
	v_mov_b32_dpp v241, v63 quad_perm:[1,0,3,2] row_mask:0xf bank_mask:0xf
	v_mov_b32_dpp v242, v64 quad_perm:[1,0,3,2] row_mask:0xf bank_mask:0xf
	v_mov_b32_dpp v243, v65 quad_perm:[1,0,3,2] row_mask:0xf bank_mask:0xf
	v_perm_b32 v240, v240, v62, v244
	v_perm_b32 v241, v241, v63, v244
	v_perm_b32 v242, v242, v64, v244
	v_perm_b32 v243, v243, v65, v244
	ds_write_b32 v34, v240 offset:17408
	ds_write_b32 v34, v241 offset:17696
	ds_write_b32 v34, v242 offset:17984
	ds_write_b32 v34, v243 offset:18272
	s_cbranch_scc1 .LBB0_1091
	v_or_b32_e32 v38, 64, v26
	v_add_u32_e32 v18, 64, v0
	v_mov_b64_e32 v[34:35], s[2:3]
	v_add_u32_e32 v20, 64, v29
	v_add_u32_e32 v36, s9, v38
	v_mad_i64_i32 v[18:19], s[12:13], v18, s57, v[34:35]
	v_mad_i64_i32 v[20:21], s[12:13], v20, s57, v[34:35]
	v_mad_i64_i32 v[36:37], s[12:13], v36, s57, v[34:35]
	v_add_u32_e32 v38, s10, v38
	v_lshl_add_u64 v[18:19], v[22:23], 1, v[18:19]
	v_lshl_add_u64 v[30:31], v[24:25], 1, v[20:21]
	v_lshl_add_u64 v[36:37], s[4:5], 1, v[36:37]
	v_mad_i64_i32 v[34:35], s[12:13], v38, s57, v[34:35]
	global_load_dwordx4 v[18:21], v[18:19], off offset:1024
	s_nop 0
	global_load_dwordx4 v[30:33], v[30:31], off offset:1024
	v_lshl_add_u64 v[34:35], s[6:7], 1, v[34:35]
	global_load_dwordx4 v[58:61], v[36:37], off offset:2048
	global_load_dwordx4 v[62:65], v[34:35], off offset:2048

; template <int D, int DV, int MODE, int NMAP, int KT> ...
;     ...
;     AT_LOAD(0);
;     __syncthreads();
;     AT_STORE(0);
;     if (nkt > 1) AT_LOAD(1);
;     for (int kt = 0; kt < nkt; ++kt) {
;         __syncthreads();
;         const int cur = (kt & 1) * BUF_BYTES;
;         if (kt + 1 < nkt) { AT_STORE(((kt + 1) & 1) * BUF_BYTES); if (kt + 2 < nkt) AT_LOAD(kt + 2); }
.LBB0_1093:
	s_add_i32 s77, s2, 1
	s_cmp_ge_i32 s77, s44
	s_waitcnt lgkmcnt(0)
	s_barrier
	s_cbranch_scc1 .LBB0_1096
	s_bitcmp1_b32 s77, 0
	s_cselect_b32 s3, 0x8c00, 0
	s_add_i32 s3, s3, 0
	v_add3_u32 v98, s3, v135, v144
	s_add_i32 s4, s3, s45
	s_waitcnt vmcnt(0)
	ds_write_b128 v98, v[18:21]
	v_add3_u32 v98, s3, v145, v146
	s_add_i32 s4, s4, s56
	s_add_i32 s3, s3, s61
	ds_write_b128 v98, v[30:33]
	v_add_u32_e32 v98, s4, v147
	s_add_i32 s3, s3, s67
	v_bfe_i32 v244, v211, 0, 1
	v_and_b32_e32 v244, 0x6060606, v244
	v_xor_b32_e32 v244, 0x5040100, v244
	v_mov_b32_dpp v240, v58 quad_perm:[1,0,3,2] row_mask:0xf bank_mask:0xf
	v_mov_b32_dpp v241, v59 quad_perm:[1,0,3,2] row_mask:0xf bank_mask:0xf
	v_mov_b32_dpp v242, v60 quad_perm:[1,0,3,2] row_mask:0xf bank_mask:0xf
	v_mov_b32_dpp v243, v61 quad_perm:[1,0,3,2] row_mask:0xf bank_mask:0xf
	v_perm_b32 v240, v240, v58, v244
	v_perm_b32 v241, v241, v59, v244
	v_perm_b32 v242, v242, v60, v244
	v_perm_b32 v243, v243, v61, v244
	ds_write_b32 v98, v240 offset:17408
	ds_write_b32 v98, v241 offset:17696
	ds_write_b32 v98, v242 offset:17984
	ds_write_b32 v98, v243 offset:18272
	v_add_u32_e32 v98, s3, v147
	s_add_i32 s3, s2, 2
	s_cmp_ge_i32 s3, s44
	v_mov_b32_dpp v240, v62 quad_perm:[1,0,3,2] row_mask:0xf bank_mask:0xf
	v_mov_b32_dpp v241, v63 quad_perm:[1,0,3,2] row_mask:0xf bank_mask:0xf
	v_mov_b32_dpp v242, v64 quad_perm:[1,0,3,2] row_mask:0xf bank_mask:0xf
	v_mov_b32_dpp v243, v65 quad_perm:[1,0,3,2] row_mask:0xf bank_mask:0xf
	v_perm_b32 v240, v240, v62, v244
	v_perm_b32 v241, v241, v63, v244
	v_perm_b32 v242, v242, v64, v244
	v_perm_b32 v243, v243, v65, v244
	ds_write_b32 v98, v240 offset:17408
	ds_write_b32 v98, v241 offset:17696
	ds_write_b32 v98, v242 offset:17984
	ds_write_b32 v98, v243 offset:18272
	s_cbranch_scc1 .LBB0_1096
	v_add_u32_e32 v60, s76, v155
	v_mov_b64_e32 v[58:59], s[48:49]
	v_add_u32_e32 v18, s76, v154
	v_add_u32_e32 v20, s76, v153
	v_mad_i64_i32 v[58:59], s[4:5], v60, s57, v[58:59]
	v_add_u32_e32 v62, s76, v156
	v_mov_b64_e32 v[60:61], s[50:51]
	v_mad_i64_i32 v[18:19], s[4:5], v18, s57, v[138:139]
	v_mad_i64_i32 v[30:31], s[4:5], v20, s57, v[140:141]
	v_mad_i64_i32 v[62:63], s[4:5], v62, s57, v[60:61]
	global_load_dwordx4 v[18:21], v[18:19], off offset:1024
	s_nop 0
	global_load_dwordx4 v[30:33], v[30:31], off offset:1024
	s_nop 0
	global_load_dwordx4 v[58:61], v[58:59], off offset:2048
	s_nop 0
	global_load_dwordx4 v[62:65], v[62:63], off offset:2048
